# same as the 4-workgroup chain sync version; chain-sync spin cap raised to 1M polls (robustness only)
# speedup vs baseline: 1.0675x; 1.0012x over previous
.Lq_poll_4:
	global_load_dword v1, v179, s[4:5] sc1
	s_waitcnt vmcnt(0)
	v_cmp_le_u32_e32 vcc, s8, v1
	s_cbranch_vccnz .Lq_done_4
	s_sleep 1
	s_add_i32 s16, s16, 1
	s_cmp_lt_u32 s16, 0x100000
	s_cbranch_scc1 .Lq_poll_4
